# static priority raise for waves 0-3 kept through the attention sample units (reset at the end of the attention phase)
# speedup vs baseline: 1.0028x; 1.0028x over previous
.LBB0_588:
	s_setprio 0
	v_readlane_b32 s34, v254, 48
	v_readlane_b32 s35, v254, 49
	v_readlane_b32 s36, v254, 51
	v_readlane_b32 s44, v254, 52
	v_readlane_b32 s4, v254, 57
	v_readlane_b32 s45, v254, 53
	v_readlane_b32 s5, v254, 58
